# nbr tiles: in-place masking, softmax VALU interleaved with PV MFMAs, 4-chain reductions
# speedup vs baseline: 1.0117x; 1.0075x over previous
; __device__ __forceinline__ unsigned pk_bf16(float lo, float hi) { unsigned r; asm volatile("v_cvt_pk_bf16_f32 %0, %1, %2" : "=v"(r) : "v"(lo), "v"(hi)); return r; }
; __device__ __forceinline__ void attn_unit(int uv, const float* sink_l, const bf16_t* P, bf16_t* Y, ATT_LAS unsigned char* lds, const float* rpb_l, const float* qn_l, const float* kn_l) {
;     ...
;                 const float mt = rowmax32(p0, p1);
;                 if (__any(mt > m)) { const float mn = fmaxf(m, mt), alpha = __builtin_amdgcn_exp2f(m - mn); m = mn; lsum *= alpha;
; #pragma unroll
;                     for (int r = 0; r < 16; ++r) { o0[r] *= alpha; o1[r] *= alpha; } }
;                 float sum = 0.f;
; #pragma unroll
;                 for (int r = 0; r < 16; ++r) { p0[r] = __builtin_amdgcn_exp2f(p0[r] - m); p1[r] = __builtin_amdgcn_exp2f(p1[r] - m); sum += p0[r] + p1[r]; }
;                 lsum += sum;
;                 u32x4 pw[4];
; #pragma unroll
;                 for (int j = 0; j < 4; ++j) { pw[0][j] = pk_bf16(p0[2 * j], p0[2 * j + 1]); pw[1][j] = pk_bf16(p0[8 + 2 * j], p0[8 + 2 * j + 1]);
;                                               pw[2][j] = pk_bf16(p1[2 * j], p1[2 * j + 1]); pw[3][j] = pk_bf16(p1[8 + 2 * j], p1[8 + 2 * j + 1]); }
.Lmk_ctx_body:
	ds_read_b64_tr_b16 v[160:161], v242 offset:24576
	ds_read_b64_tr_b16 v[162:163], v242 offset:25088
	ds_read_b64_tr_b16 v[176:177], v242 offset:28672
	ds_read_b64_tr_b16 v[178:179], v242 offset:29184
	ds_read_b64_tr_b16 v[164:165], v242 offset:25600
	ds_read_b64_tr_b16 v[166:167], v242 offset:26112
	ds_read_b64_tr_b16 v[180:181], v242 offset:29696
	s_waitcnt lgkmcnt(14)
	v_mfma_f32_32x32x16_bf16 v[80:95], v[128:131], v[96:99], 0
	ds_read_b64_tr_b16 v[182:183], v242 offset:30208
	s_waitcnt lgkmcnt(14)
	v_mfma_f32_32x32x16_bf16 v[48:63], v[132:135], v[96:99], 0
	ds_read_b64_tr_b16 v[168:169], v242 offset:26624
	s_waitcnt lgkmcnt(14)
	v_mfma_f32_32x32x16_bf16 v[80:95], v[136:139], v[100:103], v[80:95]
	ds_read_b64_tr_b16 v[170:171], v242 offset:27136
	s_waitcnt lgkmcnt(14)
	v_mfma_f32_32x32x16_bf16 v[48:63], v[140:143], v[100:103], v[48:63]
	ds_read_b64_tr_b16 v[184:185], v242 offset:30720
	s_waitcnt lgkmcnt(14)
	v_mfma_f32_32x32x16_bf16 v[80:95], v[144:147], v[104:107], v[80:95]
	ds_read_b64_tr_b16 v[186:187], v242 offset:31232
	s_waitcnt lgkmcnt(14)
	v_mfma_f32_32x32x16_bf16 v[48:63], v[148:151], v[104:107], v[48:63]
	ds_read_b64_tr_b16 v[172:173], v242 offset:27648
	s_waitcnt lgkmcnt(14)
	v_mfma_f32_32x32x16_bf16 v[80:95], v[152:155], v[108:111], v[80:95]
	ds_read_b64_tr_b16 v[174:175], v242 offset:28160
	s_waitcnt lgkmcnt(14)
	v_mfma_f32_32x32x16_bf16 v[48:63], v[156:159], v[108:111], v[48:63]
	ds_read_b64_tr_b16 v[188:189], v242 offset:31744
	s_waitcnt lgkmcnt(14)
	ds_read_b64_tr_b16 v[190:191], v242 offset:32256
	s_nop 7
	s_nop 0
	v_max3_f32 v204, v80, v84, v88
	v_max3_f32 v205, v81, v85, v89
	v_max3_f32 v208, v82, v86, v90
	v_max3_f32 v209, v83, v87, v91
	v_max3_f32 v204, v204, v92, v48
	v_max3_f32 v205, v205, v93, v49
	v_max3_f32 v208, v208, v94, v50
	v_max3_f32 v209, v209, v95, v51
	v_max3_f32 v204, v204, v52, v56
	v_max3_f32 v205, v205, v53, v57
	v_max3_f32 v208, v208, v54, v58
	v_max3_f32 v209, v209, v55, v59
	v_max_f32_e32 v204, v204, v60
	v_max_f32_e32 v205, v205, v61
	v_max_f32_e32 v208, v208, v62
	v_max_f32_e32 v209, v209, v63
	v_max3_f32 v204, v204, v205, v208
	v_max_f32_e32 v204, v204, v209
	v_mov_b32_e32 v205, v204
	s_nop 1
	v_permlane32_swap_b32_e32 v204, v205
	v_max_f32_e32 v204, v204, v205
	v_cmp_gt_f32_e32 vcc, v204, v202
	s_cbranch_vccz .Lnb_ctx_norescale
	v_max_f32_e32 v205, v202, v204
	v_sub_f32_e32 v208, v202, v205
	v_exp_f32_e32 v208, v208
	v_mov_b32_e32 v202, v205
	v_pk_mul_f32 v[0:1], v[0:1], v[208:209] op_sel_hi:[1,0]
	v_pk_mul_f32 v[2:3], v[2:3], v[208:209] op_sel_hi:[1,0]
	v_pk_mul_f32 v[4:5], v[4:5], v[208:209] op_sel_hi:[1,0]
	v_pk_mul_f32 v[6:7], v[6:7], v[208:209] op_sel_hi:[1,0]
	v_pk_mul_f32 v[8:9], v[8:9], v[208:209] op_sel_hi:[1,0]
	v_pk_mul_f32 v[10:11], v[10:11], v[208:209] op_sel_hi:[1,0]
	v_pk_mul_f32 v[12:13], v[12:13], v[208:209] op_sel_hi:[1,0]
	v_pk_mul_f32 v[14:15], v[14:15], v[208:209] op_sel_hi:[1,0]
	v_pk_mul_f32 v[16:17], v[16:17], v[208:209] op_sel_hi:[1,0]
	v_pk_mul_f32 v[18:19], v[18:19], v[208:209] op_sel_hi:[1,0]
	v_pk_mul_f32 v[20:21], v[20:21], v[208:209] op_sel_hi:[1,0]
	v_pk_mul_f32 v[22:23], v[22:23], v[208:209] op_sel_hi:[1,0]
	v_pk_mul_f32 v[24:25], v[24:25], v[208:209] op_sel_hi:[1,0]
	v_pk_mul_f32 v[26:27], v[26:27], v[208:209] op_sel_hi:[1,0]
	v_pk_mul_f32 v[28:29], v[28:29], v[208:209] op_sel_hi:[1,0]
	v_pk_mul_f32 v[30:31], v[30:31], v[208:209] op_sel_hi:[1,0]
	v_mul_f32_e32 v124, v124, v208
.Lnb_ctx_norescale:
	v_sub_f32_e32 v80, v80, v202
	v_sub_f32_e32 v81, v81, v202
	v_sub_f32_e32 v82, v82, v202
	v_sub_f32_e32 v83, v83, v202
	v_sub_f32_e32 v84, v84, v202
	v_sub_f32_e32 v85, v85, v202
	v_sub_f32_e32 v86, v86, v202
	v_sub_f32_e32 v87, v87, v202
	v_sub_f32_e32 v88, v88, v202
	v_sub_f32_e32 v89, v89, v202
	v_sub_f32_e32 v90, v90, v202
	v_sub_f32_e32 v91, v91, v202
	v_sub_f32_e32 v92, v92, v202
	v_sub_f32_e32 v93, v93, v202
	v_sub_f32_e32 v94, v94, v202
	v_sub_f32_e32 v95, v95, v202
	v_sub_f32_e32 v48, v48, v202
	v_sub_f32_e32 v49, v49, v202
	v_sub_f32_e32 v50, v50, v202
	v_sub_f32_e32 v51, v51, v202
	v_sub_f32_e32 v52, v52, v202
	v_sub_f32_e32 v53, v53, v202
	v_sub_f32_e32 v54, v54, v202
	v_sub_f32_e32 v55, v55, v202
	v_sub_f32_e32 v56, v56, v202
	v_sub_f32_e32 v57, v57, v202
	v_sub_f32_e32 v58, v58, v202
	v_sub_f32_e32 v59, v59, v202
	v_sub_f32_e32 v60, v60, v202
	v_sub_f32_e32 v61, v61, v202
	v_sub_f32_e32 v62, v62, v202
	v_sub_f32_e32 v63, v63, v202
	v_exp_f32_e32 v80, v80
	v_exp_f32_e32 v81, v81
	v_exp_f32_e32 v82, v82
	v_exp_f32_e32 v83, v83
	v_exp_f32_e32 v84, v84
	v_exp_f32_e32 v85, v85
	v_exp_f32_e32 v86, v86
	v_exp_f32_e32 v87, v87
	v_exp_f32_e32 v88, v88
	v_exp_f32_e32 v89, v89
	v_exp_f32_e32 v90, v90
	v_exp_f32_e32 v91, v91
	v_exp_f32_e32 v92, v92
	v_exp_f32_e32 v93, v93
	v_exp_f32_e32 v94, v94
	v_exp_f32_e32 v95, v95
	v_exp_f32_e32 v48, v48
	v_exp_f32_e32 v49, v49
	v_exp_f32_e32 v50, v50
	v_exp_f32_e32 v51, v51
	v_exp_f32_e32 v52, v52
	v_exp_f32_e32 v53, v53
	v_exp_f32_e32 v54, v54
	v_exp_f32_e32 v55, v55
	v_exp_f32_e32 v56, v56
	v_exp_f32_e32 v57, v57
	v_exp_f32_e32 v58, v58
	v_exp_f32_e32 v59, v59
	v_exp_f32_e32 v60, v60
	v_exp_f32_e32 v61, v61
	v_exp_f32_e32 v62, v62
	v_exp_f32_e32 v63, v63
	v_cvt_pk_bf16_f32 v32, v80, v81
	v_cvt_pk_bf16_f32 v33, v82, v83
	v_cvt_pk_bf16_f32 v34, v84, v85
	v_cvt_pk_bf16_f32 v35, v86, v87
	v_cvt_pk_bf16_f32 v36, v88, v89
	v_cvt_pk_bf16_f32 v37, v90, v91
	v_cvt_pk_bf16_f32 v38, v92, v93
	v_cvt_pk_bf16_f32 v39, v94, v95
	s_nop 1
	s_waitcnt lgkmcnt(0)
; #define ATT_LAS __attribute__((address_space(3)))
; __device__ __forceinline__ void attn_unit(int uv, const float* sink_l, const bf16_t* P, bf16_t* Y, ATT_LAS unsigned char* lds, const float* rpb_l, const float* qn_l, const float* kn_l) {
;     ...
;                 else { const int qc = 32 * (wid & 1) + r32, cs = clampi(qc - 8, 0, 48); const ATT_LAS float* trow = tbl + (tl - qr + 7) * 31 + 15 - qc;
; #pragma unroll
;                     for (int r = 0; r < 16; ++r) { const int kcl = crow(r, hi);
;                         const float b0 = trow[kcl], b1 = trow[kcl + 32];
;                         p0[r] = ((unsigned)(kcl - cs) < 16u) ? p0[r] + b0 : NEGF;
;                         p1[r] = ((unsigned)(kcl + 32 - cs) < 16u) ? p1[r] + b1 : NEGF; } }
;                 const float mt = rowmax32(p0, p1);
;                 if (__any(mt > m)) { const float mn = fmaxf(m, mt), alpha = __builtin_amdgcn_exp2f(m - mn); m = mn; lsum *= alpha;
;     ...
;                 float sum = 0.f;
; #pragma unroll
;                 for (int r = 0; r < 16; ++r) { p0[r] = __builtin_amdgcn_exp2f(p0[r] - m); p1[r] = __builtin_amdgcn_exp2f(p1[r] - m); sum += p0[r] + p1[r]; }
;                 lsum += sum;
;                 u32x4 pw[4];
; #pragma unroll
;                 for (int j = 0; j < 4; ++j) { pw[0][j] = pk_bf16(p0[2 * j], p0[2 * j + 1]); pw[1][j] = pk_bf16(p0[8 + 2 * j], p0[8 + 2 * j + 1]);
;                                               pw[2][j] = pk_bf16(p1[2 * j], p1[2 * j + 1]); pw[3][j] = pk_bf16(p1[8 + 2 * j], p1[8 + 2 * j + 1]); }
;                 const ATT_LAS unsigned char* vb = Vb + vlane;
; #pragma unroll
;                 for (int s = 0; s < 4; ++s) {
;                     const bf16x8 pa = __builtin_bit_cast(bf16x8, pw[s]);
;                     { const s16x4 lo = vtr(vb + s * 1024), h4 = vtr(vb + s * 1024 + 512);
;                       const bf16x8 vf = (bf16x8){lo[0], lo[1], lo[2], lo[3], h4[0], h4[1], h4[2], h4[3]};
;                       o0 = __builtin_amdgcn_mfma_f32_32x32x16_bf16(vf, pa, o0, 0, 0, 0); }
;                     { const s16x4 lo = vtr(vb + 4096 + s * 1024), h4 = vtr(vb + 4096 + s * 1024 + 512);
;                       const bf16x8 vf = (bf16x8){lo[0], lo[1], lo[2], lo[3], h4[0], h4[1], h4[2], h4[3]};
;                       o1 = __builtin_amdgcn_mfma_f32_32x32x16_bf16(vf, pa, o1, 0, 0, 0); }
;                 }
	v_mfma_f32_32x32x16_bf16 v[0:15], v[160:163], v[32:35], v[0:15]
	v_cvt_pk_bf16_f32 v40, v48, v49
	v_cvt_pk_bf16_f32 v41, v50, v51
	v_cvt_pk_bf16_f32 v42, v52, v53
	v_cvt_pk_bf16_f32 v43, v54, v55
	v_mfma_f32_32x32x16_bf16 v[16:31], v[176:179], v[32:35], v[16:31]
	v_mov_b32_e32 v204, v80
	v_mov_b32_e32 v205, v81
	v_mov_b32_e32 v208, v82
	v_mov_b32_e32 v209, v83
	v_add_f32_e32 v204, v204, v84
	v_add_f32_e32 v205, v205, v85
	v_add_f32_e32 v208, v208, v86
	v_add_f32_e32 v209, v209, v87
	v_add_f32_e32 v204, v204, v88
	v_mfma_f32_32x32x16_bf16 v[0:15], v[164:167], v[36:39], v[0:15]
	v_cvt_pk_bf16_f32 v44, v56, v57
	v_cvt_pk_bf16_f32 v45, v58, v59
	v_cvt_pk_bf16_f32 v46, v60, v61
	v_cvt_pk_bf16_f32 v47, v62, v63
	v_mfma_f32_32x32x16_bf16 v[16:31], v[180:183], v[36:39], v[16:31]
	v_add_f32_e32 v205, v205, v89
	v_add_f32_e32 v208, v208, v90
	v_add_f32_e32 v209, v209, v91
	v_add_f32_e32 v204, v204, v92
	v_add_f32_e32 v205, v205, v93
	v_add_f32_e32 v208, v208, v94
	v_add_f32_e32 v209, v209, v95
	v_add_f32_e32 v204, v204, v48
	v_add_f32_e32 v205, v205, v49
	v_mfma_f32_32x32x16_bf16 v[0:15], v[168:171], v[40:43], v[0:15]
	v_mfma_f32_32x32x16_bf16 v[16:31], v[184:187], v[40:43], v[16:31]
	v_add_f32_e32 v208, v208, v50
	v_add_f32_e32 v209, v209, v51
	v_add_f32_e32 v204, v204, v52
	v_add_f32_e32 v205, v205, v53
	v_add_f32_e32 v208, v208, v54
	v_add_f32_e32 v209, v209, v55
	v_add_f32_e32 v204, v204, v56
	v_add_f32_e32 v205, v205, v57
	v_add_f32_e32 v208, v208, v58
	v_mfma_f32_32x32x16_bf16 v[0:15], v[172:175], v[44:47], v[0:15]
	v_mfma_f32_32x32x16_bf16 v[16:31], v[188:191], v[44:47], v[16:31]
	v_add_f32_e32 v209, v209, v59
	v_add_f32_e32 v204, v204, v60
	v_add_f32_e32 v205, v205, v61
	v_add_f32_e32 v208, v208, v62
	v_add_f32_e32 v209, v209, v63
	v_add_f32_e32 v204, v204, v205
	v_add_f32_e32 v208, v208, v209
	v_add_f32_e32 v204, v204, v208
	v_add_f32_e32 v124, v124, v204
	s_branch .Lmsk_tail
.Lmk_lat:
	s_and_b64 vcc, exec, s[2:3]
	s_cbranch_vccz .Lmsk_win
	v_readfirstlane_b32 vcc_lo, v192
	s_nop 0
	s_bitcmp1_b32 vcc_lo, 6
	s_cbranch_scc1 .Lnb_odd
	ds_read2_b32 v[32:33], v127 offset1:1
	ds_read2_b32 v[34:35], v127 offset0:2 offset1:3
	ds_read2_b32 v[36:37], v127 offset0:8 offset1:9
	ds_read2_b32 v[38:39], v127 offset0:10 offset1:11
	ds_read2_b32 v[40:41], v127 offset0:16 offset1:17
	ds_read2_b32 v[42:43], v127 offset0:18 offset1:19
	ds_read2_b32 v[44:45], v127 offset0:24 offset1:25
	s_waitcnt lgkmcnt(14)
	v_mfma_f32_32x32x16_bf16 v[80:95], v[128:131], v[96:99], 0
	ds_read2_b32 v[46:47], v127 offset0:26 offset1:27
	s_waitcnt lgkmcnt(14)
	v_mfma_f32_32x32x16_bf16 v[48:63], v[132:135], v[96:99], 0
	ds_read2_b32 v[64:65], v127 offset0:32 offset1:33
	s_waitcnt lgkmcnt(14)
	v_mfma_f32_32x32x16_bf16 v[80:95], v[136:139], v[100:103], v[80:95]
	ds_read2_b32 v[66:67], v127 offset0:34 offset1:35
	s_waitcnt lgkmcnt(14)
	v_mfma_f32_32x32x16_bf16 v[48:63], v[140:143], v[100:103], v[48:63]
	ds_read_b64_tr_b16 v[160:161], v242 offset:24576
	s_waitcnt lgkmcnt(14)
	v_mfma_f32_32x32x16_bf16 v[80:95], v[144:147], v[104:107], v[80:95]
	ds_read_b64_tr_b16 v[162:163], v242 offset:25088
	s_waitcnt lgkmcnt(14)
	v_mfma_f32_32x32x16_bf16 v[48:63], v[148:151], v[104:107], v[48:63]
	ds_read_b64_tr_b16 v[176:177], v242 offset:28672
	s_waitcnt lgkmcnt(14)
	v_mfma_f32_32x32x16_bf16 v[80:95], v[152:155], v[108:111], v[80:95]
	ds_read_b64_tr_b16 v[178:179], v242 offset:29184
	s_waitcnt lgkmcnt(14)
	v_mfma_f32_32x32x16_bf16 v[48:63], v[156:159], v[108:111], v[48:63]
	ds_read_b64_tr_b16 v[164:165], v242 offset:25600
	s_waitcnt lgkmcnt(14)
	ds_read_b64_tr_b16 v[166:167], v242 offset:26112
	s_nop 5
	v_add_f32_e32 v80, v80, v32
	v_add_f32_e32 v81, v81, v33
	v_cndmask_b32_e64 v80, v216, v80, s[0:1]
	v_cndmask_b32_e64 v81, v216, v81, s[4:5]
	s_waitcnt lgkmcnt(14)
	ds_read_b64_tr_b16 v[180:181], v242 offset:29696
	v_add_f32_e32 v82, v82, v34
	v_add_f32_e32 v83, v83, v35
	v_cndmask_b32_e64 v82, v216, v82, s[10:11]
	v_cndmask_b32_e64 v83, v216, v83, s[14:15]
	s_waitcnt lgkmcnt(14)
	ds_read_b64_tr_b16 v[182:183], v242 offset:30208
	v_add_f32_e32 v84, v84, v36
	v_add_f32_e32 v85, v85, v37
	v_cndmask_b32_e64 v84, v216, v84, s[18:19]
	v_cndmask_b32_e64 v85, v216, v85, s[22:23]
	s_waitcnt lgkmcnt(14)
	ds_read_b64_tr_b16 v[168:169], v242 offset:26624
	v_add_f32_e32 v86, v86, v38
	v_add_f32_e32 v87, v87, v39
	v_cndmask_b32_e64 v86, v216, v86, s[26:27]
	v_cndmask_b32_e64 v87, v216, v87, s[30:31]
	s_waitcnt lgkmcnt(14)
	ds_read_b64_tr_b16 v[170:171], v242 offset:27136
	v_add_f32_e32 v88, v88, v40
	v_add_f32_e32 v89, v89, v41
	v_cndmask_b32_e64 v88, v216, v88, s[76:77]
	v_cndmask_b32_e64 v89, v216, v89, s[40:41]
	s_waitcnt lgkmcnt(14)
	ds_read_b64_tr_b16 v[184:185], v242 offset:30720
	v_add_f32_e32 v90, v90, v42
	v_add_f32_e32 v91, v91, v43
	v_cndmask_b32_e64 v90, v216, v90, s[44:45]
	v_cndmask_b32_e64 v91, v216, v91, s[48:49]
	s_waitcnt lgkmcnt(14)
	ds_read_b64_tr_b16 v[186:187], v242 offset:31232
	v_add_f32_e32 v92, v92, v44
	v_add_f32_e32 v93, v93, v45
	v_cndmask_b32_e64 v92, v216, v92, s[52:53]
	v_cndmask_b32_e64 v93, v216, v93, s[56:57]
	s_waitcnt lgkmcnt(14)
	v_add_f32_e32 v94, v94, v46
	v_add_f32_e32 v95, v95, v47
	v_cndmask_b32_e64 v94, v216, v94, s[60:61]
	v_cndmask_b32_e64 v95, v216, v95, s[64:65]
	s_waitcnt lgkmcnt(13)
	v_add_f32_e32 v48, v48, v64
	v_add_f32_e32 v49, v49, v65
	v_cndmask_b32_e64 v48, v216, v48, s[68:69]
	v_cndmask_b32_e64 v49, v216, v49, s[8:9]
	s_waitcnt lgkmcnt(12)
	v_add_f32_e32 v50, v50, v66
	v_add_f32_e32 v51, v51, v67
	v_cndmask_b32_e64 v50, v216, v50, s[12:13]
	v_cndmask_b32_e64 v51, v216, v51, s[16:17]
	v_max3_f32 v204, v80, v84, v88
	v_max3_f32 v205, v81, v85, v89
	v_max3_f32 v208, v82, v86, v90
	v_max3_f32 v209, v83, v87, v91
	v_max3_f32 v204, v204, v92, v48
	v_max3_f32 v205, v205, v93, v49
	v_max3_f32 v208, v208, v94, v50
	v_max3_f32 v209, v209, v95, v51
	v_max3_f32 v204, v204, v205, v208
	v_max_f32_e32 v204, v204, v209
	v_mov_b32_e32 v205, v204
	s_nop 1
	v_permlane32_swap_b32_e32 v204, v205
	v_max_f32_e32 v204, v204, v205
	v_cmp_gt_f32_e32 vcc, v204, v202
	s_cbranch_vccz .Lnb_even_norescale
; #define ATT_LAS __attribute__((address_space(3)))
; __device__ __forceinline__ unsigned pk_bf16(float lo, float hi) { unsigned r; asm volatile("v_cvt_pk_bf16_f32 %0, %1, %2" : "=v"(r) : "v"(lo), "v"(hi)); return r; }
; __device__ __forceinline__ void attn_unit(int uv, const float* sink_l, const bf16_t* P, bf16_t* Y, ATT_LAS unsigned char* lds, const float* rpb_l, const float* qn_l, const float* kn_l) {
;     ...
;                 if (__any(mt > m)) { const float mn = fmaxf(m, mt), alpha = __builtin_amdgcn_exp2f(m - mn); m = mn; lsum *= alpha;
; #pragma unroll
;                     for (int r = 0; r < 16; ++r) { o0[r] *= alpha; o1[r] *= alpha; } }
;                 float sum = 0.f;
; #pragma unroll
;                 for (int r = 0; r < 16; ++r) { p0[r] = __builtin_amdgcn_exp2f(p0[r] - m); p1[r] = __builtin_amdgcn_exp2f(p1[r] - m); sum += p0[r] + p1[r]; }
;                 lsum += sum;
;                 u32x4 pw[4];
; #pragma unroll
;                 for (int j = 0; j < 4; ++j) { pw[0][j] = pk_bf16(p0[2 * j], p0[2 * j + 1]); pw[1][j] = pk_bf16(p0[8 + 2 * j], p0[8 + 2 * j + 1]);
;                                               pw[2][j] = pk_bf16(p1[2 * j], p1[2 * j + 1]); pw[3][j] = pk_bf16(p1[8 + 2 * j], p1[8 + 2 * j + 1]); }
;                 const ATT_LAS unsigned char* vb = Vb + vlane;
; #pragma unroll
;                 for (int s = 0; s < 4; ++s) {
;                     const bf16x8 pa = __builtin_bit_cast(bf16x8, pw[s]);
;                     { const s16x4 lo = vtr(vb + s * 1024), h4 = vtr(vb + s * 1024 + 512);
;                       const bf16x8 vf = (bf16x8){lo[0], lo[1], lo[2], lo[3], h4[0], h4[1], h4[2], h4[3]};
;                       o0 = __builtin_amdgcn_mfma_f32_32x32x16_bf16(vf, pa, o0, 0, 0, 0); }
;                     { const s16x4 lo = vtr(vb + 4096 + s * 1024), h4 = vtr(vb + 4096 + s * 1024 + 512);
;                       const bf16x8 vf = (bf16x8){lo[0], lo[1], lo[2], lo[3], h4[0], h4[1], h4[2], h4[3]};
;                       o1 = __builtin_amdgcn_mfma_f32_32x32x16_bf16(vf, pa, o1, 0, 0, 0); }
;                 }
	v_max_f32_e32 v205, v202, v204
	v_sub_f32_e32 v208, v202, v205
	v_exp_f32_e32 v208, v208
	v_mov_b32_e32 v202, v205
	v_pk_mul_f32 v[0:1], v[0:1], v[208:209] op_sel_hi:[1,0]
	v_pk_mul_f32 v[2:3], v[2:3], v[208:209] op_sel_hi:[1,0]
	v_pk_mul_f32 v[4:5], v[4:5], v[208:209] op_sel_hi:[1,0]
	v_pk_mul_f32 v[6:7], v[6:7], v[208:209] op_sel_hi:[1,0]
	v_pk_mul_f32 v[8:9], v[8:9], v[208:209] op_sel_hi:[1,0]
	v_pk_mul_f32 v[10:11], v[10:11], v[208:209] op_sel_hi:[1,0]
	v_pk_mul_f32 v[12:13], v[12:13], v[208:209] op_sel_hi:[1,0]
	v_pk_mul_f32 v[14:15], v[14:15], v[208:209] op_sel_hi:[1,0]
	v_pk_mul_f32 v[16:17], v[16:17], v[208:209] op_sel_hi:[1,0]
	v_pk_mul_f32 v[18:19], v[18:19], v[208:209] op_sel_hi:[1,0]
	v_pk_mul_f32 v[20:21], v[20:21], v[208:209] op_sel_hi:[1,0]
	v_pk_mul_f32 v[22:23], v[22:23], v[208:209] op_sel_hi:[1,0]
	v_pk_mul_f32 v[24:25], v[24:25], v[208:209] op_sel_hi:[1,0]
	v_pk_mul_f32 v[26:27], v[26:27], v[208:209] op_sel_hi:[1,0]
	v_pk_mul_f32 v[28:29], v[28:29], v[208:209] op_sel_hi:[1,0]
	v_pk_mul_f32 v[30:31], v[30:31], v[208:209] op_sel_hi:[1,0]
	v_mul_f32_e32 v124, v124, v208
.Lnb_even_norescale:
	v_sub_f32_e32 v80, v80, v202
	v_sub_f32_e32 v81, v81, v202
	v_sub_f32_e32 v82, v82, v202
	v_sub_f32_e32 v83, v83, v202
	v_sub_f32_e32 v84, v84, v202
	v_sub_f32_e32 v85, v85, v202
	v_sub_f32_e32 v86, v86, v202
	v_sub_f32_e32 v87, v87, v202
	v_sub_f32_e32 v88, v88, v202
	v_sub_f32_e32 v89, v89, v202
	v_sub_f32_e32 v90, v90, v202
	v_sub_f32_e32 v91, v91, v202
	v_sub_f32_e32 v92, v92, v202
	v_sub_f32_e32 v93, v93, v202
	v_sub_f32_e32 v94, v94, v202
	v_sub_f32_e32 v95, v95, v202
	v_sub_f32_e32 v48, v48, v202
	v_sub_f32_e32 v49, v49, v202
	v_sub_f32_e32 v50, v50, v202
	v_sub_f32_e32 v51, v51, v202
	v_exp_f32_e32 v80, v80
	v_exp_f32_e32 v81, v81
	v_exp_f32_e32 v82, v82
	v_exp_f32_e32 v83, v83
	v_exp_f32_e32 v84, v84
	v_exp_f32_e32 v85, v85
	v_exp_f32_e32 v86, v86
	v_exp_f32_e32 v87, v87
	v_exp_f32_e32 v88, v88
	v_exp_f32_e32 v89, v89
	v_exp_f32_e32 v90, v90
	v_exp_f32_e32 v91, v91
	v_exp_f32_e32 v92, v92
	v_exp_f32_e32 v93, v93
	v_exp_f32_e32 v94, v94
	v_exp_f32_e32 v95, v95
	v_exp_f32_e32 v48, v48
	v_exp_f32_e32 v49, v49
	v_exp_f32_e32 v50, v50
	v_exp_f32_e32 v51, v51
	v_mov_b32_e32 v42, 0
	v_mov_b32_e32 v43, 0
	v_cvt_pk_bf16_f32 v32, v80, v81
	v_cvt_pk_bf16_f32 v33, v82, v83
	v_cvt_pk_bf16_f32 v34, v84, v85
	v_cvt_pk_bf16_f32 v35, v86, v87
	v_cvt_pk_bf16_f32 v36, v88, v89
	v_cvt_pk_bf16_f32 v37, v90, v91
	v_cvt_pk_bf16_f32 v38, v92, v93
	v_cvt_pk_bf16_f32 v39, v94, v95
	s_nop 1
	s_waitcnt lgkmcnt(0)
	v_mfma_f32_32x32x16_bf16 v[0:15], v[160:163], v[32:35], v[0:15]
	v_cvt_pk_bf16_f32 v40, v48, v49
	v_cvt_pk_bf16_f32 v41, v50, v51
	v_mfma_f32_32x32x16_bf16 v[16:31], v[176:179], v[32:35], v[16:31]
	v_mov_b32_e32 v204, v80
	v_mov_b32_e32 v205, v81
	v_mov_b32_e32 v208, v82
	v_mov_b32_e32 v209, v83
	v_add_f32_e32 v204, v204, v84
	v_add_f32_e32 v205, v205, v85
	v_add_f32_e32 v208, v208, v86
	v_add_f32_e32 v209, v209, v87
	v_mfma_f32_32x32x16_bf16 v[0:15], v[164:167], v[36:39], v[0:15]
	v_mfma_f32_32x32x16_bf16 v[16:31], v[180:183], v[36:39], v[16:31]
	v_add_f32_e32 v204, v204, v88
	v_add_f32_e32 v205, v205, v89
	v_add_f32_e32 v208, v208, v90
	v_add_f32_e32 v209, v209, v91
	v_add_f32_e32 v204, v204, v92
	v_add_f32_e32 v205, v205, v93
	v_add_f32_e32 v208, v208, v94
	v_add_f32_e32 v209, v209, v95
	v_mfma_f32_32x32x16_bf16 v[0:15], v[168:171], v[40:43], v[0:15]
	v_mfma_f32_32x32x16_bf16 v[16:31], v[184:187], v[40:43], v[16:31]
	v_add_f32_e32 v204, v204, v48
	v_add_f32_e32 v205, v205, v49
	v_add_f32_e32 v208, v208, v50
	v_add_f32_e32 v209, v209, v51
	v_add_f32_e32 v204, v204, v205
	v_add_f32_e32 v208, v208, v209
	v_add_f32_e32 v204, v204, v208
	v_add_f32_e32 v124, v124, v204
	s_branch .Lmsk_tail
.Lnb_odd:
	ds_read2_b32 v[64:65], v127 offset0:32 offset1:33
	ds_read2_b32 v[66:67], v127 offset0:34 offset1:35
	ds_read2_b32 v[68:69], v127 offset0:40 offset1:41
	ds_read2_b32 v[70:71], v127 offset0:42 offset1:43
	ds_read2_b32 v[72:73], v127 offset0:48 offset1:49
	ds_read2_b32 v[74:75], v127 offset0:50 offset1:51
	ds_read2_b32 v[76:77], v127 offset0:56 offset1:57
	s_waitcnt lgkmcnt(14)
	v_mfma_f32_32x32x16_bf16 v[80:95], v[128:131], v[96:99], 0
	ds_read2_b32 v[78:79], v127 offset0:58 offset1:59
	s_waitcnt lgkmcnt(14)
	v_mfma_f32_32x32x16_bf16 v[48:63], v[132:135], v[96:99], 0
	ds_read2_b32 v[44:45], v127 offset0:24 offset1:25
	s_waitcnt lgkmcnt(14)
	v_mfma_f32_32x32x16_bf16 v[80:95], v[136:139], v[100:103], v[80:95]
	ds_read2_b32 v[46:47], v127 offset0:26 offset1:27
	s_waitcnt lgkmcnt(14)
	v_mfma_f32_32x32x16_bf16 v[48:63], v[140:143], v[100:103], v[48:63]
	ds_read_b64_tr_b16 v[164:165], v242 offset:25600
	s_waitcnt lgkmcnt(14)
	v_mfma_f32_32x32x16_bf16 v[80:95], v[144:147], v[104:107], v[80:95]
	ds_read_b64_tr_b16 v[166:167], v242 offset:26112
	s_waitcnt lgkmcnt(14)
	v_mfma_f32_32x32x16_bf16 v[48:63], v[148:151], v[104:107], v[48:63]
	ds_read_b64_tr_b16 v[180:181], v242 offset:29696
	s_waitcnt lgkmcnt(14)
	v_mfma_f32_32x32x16_bf16 v[80:95], v[152:155], v[108:111], v[80:95]
	ds_read_b64_tr_b16 v[182:183], v242 offset:30208
	s_waitcnt lgkmcnt(14)
	v_mfma_f32_32x32x16_bf16 v[48:63], v[156:159], v[108:111], v[48:63]
	ds_read_b64_tr_b16 v[168:169], v242 offset:26624
	s_waitcnt lgkmcnt(14)
	ds_read_b64_tr_b16 v[170:171], v242 offset:27136
	s_nop 7
	s_nop 0
	v_add_f32_e32 v48, v48, v64
	v_add_f32_e32 v49, v49, v65
	v_cndmask_b32_e64 v48, v216, v48, s[68:69]
	v_cndmask_b32_e64 v49, v216, v49, s[8:9]
	s_waitcnt lgkmcnt(14)
	ds_read_b64_tr_b16 v[184:185], v242 offset:30720
	v_add_f32_e32 v50, v50, v66
	v_add_f32_e32 v51, v51, v67
	v_cndmask_b32_e64 v50, v216, v50, s[12:13]
	v_cndmask_b32_e64 v51, v216, v51, s[16:17]
	s_waitcnt lgkmcnt(14)
; __device__ __forceinline__ void attn_unit(int uv, const float* sink_l, const bf16_t* P, bf16_t* Y, ATT_LAS unsigned char* lds, const float* rpb_l, const float* qn_l, const float* kn_l) {
;     ...
;                 else { const int qc = 32 * (wid & 1) + r32, cs = clampi(qc - 8, 0, 48); const ATT_LAS float* trow = tbl + (tl - qr + 7) * 31 + 15 - qc;
; #pragma unroll
;                     for (int r = 0; r < 16; ++r) { const int kcl = crow(r, hi);
;                         const float b0 = trow[kcl], b1 = trow[kcl + 32];
;                         p0[r] = ((unsigned)(kcl - cs) < 16u) ? p0[r] + b0 : NEGF;
;                         p1[r] = ((unsigned)(kcl + 32 - cs) < 16u) ? p1[r] + b1 : NEGF; } }
;                 const float mt = rowmax32(p0, p1);
;                 if (__any(mt > m)) { const float mn = fmaxf(m, mt), alpha = __builtin_amdgcn_exp2f(m - mn); m = mn; lsum *= alpha;
; #pragma unroll
;                     for (int r = 0; r < 16; ++r) { o0[r] *= alpha; o1[r] *= alpha; } }
;                 float sum = 0.f;
; #pragma unroll
;                 for (int r = 0; r < 16; ++r) { p0[r] = __builtin_amdgcn_exp2f(p0[r] - m); p1[r] = __builtin_amdgcn_exp2f(p1[r] - m); sum += p0[r] + p1[r]; }
;                 lsum += sum;
;                 u32x4 pw[4];
; #pragma unroll
;                 for (int j = 0; j < 4; ++j) { pw[0][j] = pk_bf16(p0[2 * j], p0[2 * j + 1]); pw[1][j] = pk_bf16(p0[8 + 2 * j], p0[8 + 2 * j + 1]);
;                                               pw[2][j] = pk_bf16(p1[2 * j], p1[2 * j + 1]); pw[3][j] = pk_bf16(p1[8 + 2 * j], p1[8 + 2 * j + 1]); }
;                 const ATT_LAS unsigned char* vb = Vb + vlane;
; #pragma unroll
;                 for (int s = 0; s < 4; ++s) {
;                     const bf16x8 pa = __builtin_bit_cast(bf16x8, pw[s]);
;                     { const s16x4 lo = vtr(vb + s * 1024), h4 = vtr(vb + s * 1024 + 512);
;                       const bf16x8 vf = (bf16x8){lo[0], lo[1], lo[2], lo[3], h4[0], h4[1], h4[2], h4[3]};
;                       o0 = __builtin_amdgcn_mfma_f32_32x32x16_bf16(vf, pa, o0, 0, 0, 0); }
;                     { const s16x4 lo = vtr(vb + 4096 + s * 1024), h4 = vtr(vb + 4096 + s * 1024 + 512);
;                       const bf16x8 vf = (bf16x8){lo[0], lo[1], lo[2], lo[3], h4[0], h4[1], h4[2], h4[3]};
;                       o1 = __builtin_amdgcn_mfma_f32_32x32x16_bf16(vf, pa, o1, 0, 0, 0); }
;                 }
	ds_read_b64_tr_b16 v[186:187], v242 offset:31232
	v_add_f32_e32 v52, v52, v68
	v_add_f32_e32 v53, v53, v69
	v_cndmask_b32_e64 v52, v216, v52, s[20:21]
	v_cndmask_b32_e64 v53, v216, v53, s[24:25]
	s_waitcnt lgkmcnt(14)
	ds_read_b64_tr_b16 v[172:173], v242 offset:27648
	v_add_f32_e32 v54, v54, v70
	v_add_f32_e32 v55, v55, v71
	v_cndmask_b32_e64 v54, v216, v54, s[28:29]
	v_cndmask_b32_e64 v55, v216, v55, s[94:95]
	s_waitcnt lgkmcnt(14)
	ds_read_b64_tr_b16 v[174:175], v242 offset:28160
	v_add_f32_e32 v56, v56, v72
	v_add_f32_e32 v57, v57, v73
	v_cndmask_b32_e64 v56, v216, v56, s[38:39]
	v_cndmask_b32_e64 v57, v216, v57, s[42:43]
	s_waitcnt lgkmcnt(14)
	ds_read_b64_tr_b16 v[188:189], v242 offset:31744
	v_add_f32_e32 v58, v58, v74
	v_add_f32_e32 v59, v59, v75
	v_cndmask_b32_e64 v58, v216, v58, s[46:47]
	v_cndmask_b32_e64 v59, v216, v59, s[50:51]
	s_waitcnt lgkmcnt(14)
	ds_read_b64_tr_b16 v[190:191], v242 offset:32256
	v_add_f32_e32 v60, v60, v76
	v_add_f32_e32 v61, v61, v77
	v_cndmask_b32_e64 v60, v216, v60, s[54:55]
	v_cndmask_b32_e64 v61, v216, v61, s[58:59]
	s_waitcnt lgkmcnt(14)
	v_add_f32_e32 v62, v62, v78
	v_add_f32_e32 v63, v63, v79
	v_cndmask_b32_e64 v62, v216, v62, s[62:63]
	v_cndmask_b32_e64 v63, v216, v63, s[66:67]
	s_waitcnt lgkmcnt(13)
	v_add_f32_e32 v92, v92, v44
	v_add_f32_e32 v93, v93, v45
	v_cndmask_b32_e64 v92, v216, v92, s[52:53]
	v_cndmask_b32_e64 v93, v216, v93, s[56:57]
	s_waitcnt lgkmcnt(12)
	v_add_f32_e32 v94, v94, v46
	v_add_f32_e32 v95, v95, v47
	v_cndmask_b32_e64 v94, v216, v94, s[60:61]
	v_cndmask_b32_e64 v95, v216, v95, s[64:65]
	v_max3_f32 v204, v92, v48, v52
	v_max3_f32 v205, v93, v49, v53
	v_max3_f32 v208, v94, v50, v54
	v_max3_f32 v209, v95, v51, v55
	v_max3_f32 v204, v204, v56, v60
	v_max3_f32 v205, v205, v57, v61
	v_max3_f32 v208, v208, v58, v62
	v_max3_f32 v209, v209, v59, v63
	v_max3_f32 v204, v204, v205, v208
	v_max_f32_e32 v204, v204, v209
	v_mov_b32_e32 v205, v204
	s_nop 1
	v_permlane32_swap_b32_e32 v204, v205
	v_max_f32_e32 v204, v204, v205
	v_cmp_gt_f32_e32 vcc, v204, v202
	s_cbranch_vccz .Lnb_odd_norescale
	v_max_f32_e32 v205, v202, v204
	v_sub_f32_e32 v208, v202, v205
	v_exp_f32_e32 v208, v208
	v_mov_b32_e32 v202, v205
	v_pk_mul_f32 v[0:1], v[0:1], v[208:209] op_sel_hi:[1,0]
	v_pk_mul_f32 v[2:3], v[2:3], v[208:209] op_sel_hi:[1,0]
	v_pk_mul_f32 v[4:5], v[4:5], v[208:209] op_sel_hi:[1,0]
	v_pk_mul_f32 v[6:7], v[6:7], v[208:209] op_sel_hi:[1,0]
	v_pk_mul_f32 v[8:9], v[8:9], v[208:209] op_sel_hi:[1,0]
	v_pk_mul_f32 v[10:11], v[10:11], v[208:209] op_sel_hi:[1,0]
	v_pk_mul_f32 v[12:13], v[12:13], v[208:209] op_sel_hi:[1,0]
	v_pk_mul_f32 v[14:15], v[14:15], v[208:209] op_sel_hi:[1,0]
	v_pk_mul_f32 v[16:17], v[16:17], v[208:209] op_sel_hi:[1,0]
	v_pk_mul_f32 v[18:19], v[18:19], v[208:209] op_sel_hi:[1,0]
	v_pk_mul_f32 v[20:21], v[20:21], v[208:209] op_sel_hi:[1,0]
	v_pk_mul_f32 v[22:23], v[22:23], v[208:209] op_sel_hi:[1,0]
	v_pk_mul_f32 v[24:25], v[24:25], v[208:209] op_sel_hi:[1,0]
	v_pk_mul_f32 v[26:27], v[26:27], v[208:209] op_sel_hi:[1,0]
	v_pk_mul_f32 v[28:29], v[28:29], v[208:209] op_sel_hi:[1,0]
	v_pk_mul_f32 v[30:31], v[30:31], v[208:209] op_sel_hi:[1,0]
	v_mul_f32_e32 v124, v124, v208
.Lnb_odd_norescale:
	v_sub_f32_e32 v92, v92, v202
	v_sub_f32_e32 v93, v93, v202
	v_sub_f32_e32 v94, v94, v202
	v_sub_f32_e32 v95, v95, v202
	v_sub_f32_e32 v48, v48, v202
	v_sub_f32_e32 v49, v49, v202
	v_sub_f32_e32 v50, v50, v202
	v_sub_f32_e32 v51, v51, v202
	v_sub_f32_e32 v52, v52, v202
	v_sub_f32_e32 v53, v53, v202
	v_sub_f32_e32 v54, v54, v202
	v_sub_f32_e32 v55, v55, v202
	v_sub_f32_e32 v56, v56, v202
	v_sub_f32_e32 v57, v57, v202
	v_sub_f32_e32 v58, v58, v202
	v_sub_f32_e32 v59, v59, v202
	v_sub_f32_e32 v60, v60, v202
	v_sub_f32_e32 v61, v61, v202
	v_sub_f32_e32 v62, v62, v202
	v_sub_f32_e32 v63, v63, v202
	v_exp_f32_e32 v92, v92
	v_exp_f32_e32 v93, v93
	v_exp_f32_e32 v94, v94
	v_exp_f32_e32 v95, v95
	v_exp_f32_e32 v48, v48
	v_exp_f32_e32 v49, v49
	v_exp_f32_e32 v50, v50
	v_exp_f32_e32 v51, v51
	v_exp_f32_e32 v52, v52
	v_exp_f32_e32 v53, v53
	v_exp_f32_e32 v54, v54
	v_exp_f32_e32 v55, v55
	v_exp_f32_e32 v56, v56
	v_exp_f32_e32 v57, v57
	v_exp_f32_e32 v58, v58
	v_exp_f32_e32 v59, v59
	v_exp_f32_e32 v60, v60
	v_exp_f32_e32 v61, v61
	v_exp_f32_e32 v62, v62
	v_exp_f32_e32 v63, v63
	v_mov_b32_e32 v36, 0
	v_mov_b32_e32 v37, 0
	v_cvt_pk_bf16_f32 v38, v92, v93
	v_cvt_pk_bf16_f32 v39, v94, v95
	v_cvt_pk_bf16_f32 v40, v48, v49
	v_cvt_pk_bf16_f32 v41, v50, v51
	v_cvt_pk_bf16_f32 v42, v52, v53
	v_cvt_pk_bf16_f32 v43, v54, v55
	s_nop 1
	s_waitcnt lgkmcnt(0)
	v_mfma_f32_32x32x16_bf16 v[0:15], v[164:167], v[36:39], v[0:15]
	v_cvt_pk_bf16_f32 v44, v56, v57
	v_cvt_pk_bf16_f32 v45, v58, v59
	v_cvt_pk_bf16_f32 v46, v60, v61
	v_cvt_pk_bf16_f32 v47, v62, v63
	v_mfma_f32_32x32x16_bf16 v[16:31], v[180:183], v[36:39], v[16:31]
	v_mov_b32_e32 v204, v92
	v_mov_b32_e32 v205, v93
	v_mov_b32_e32 v208, v94
	v_mov_b32_e32 v209, v95
	v_add_f32_e32 v204, v204, v48
	v_add_f32_e32 v205, v205, v49
	v_add_f32_e32 v208, v208, v50
	v_add_f32_e32 v209, v209, v51
	v_mfma_f32_32x32x16_bf16 v[0:15], v[168:171], v[40:43], v[0:15]
	v_mfma_f32_32x32x16_bf16 v[16:31], v[184:187], v[40:43], v[16:31]
	v_add_f32_e32 v204, v204, v52
	v_add_f32_e32 v205, v205, v53
	v_add_f32_e32 v208, v208, v54
	v_add_f32_e32 v209, v209, v55
	v_add_f32_e32 v204, v204, v56
	v_add_f32_e32 v205, v205, v57
	v_add_f32_e32 v208, v208, v58
	v_add_f32_e32 v209, v209, v59
	v_mfma_f32_32x32x16_bf16 v[0:15], v[172:175], v[44:47], v[0:15]
	v_mfma_f32_32x32x16_bf16 v[16:31], v[188:191], v[44:47], v[16:31]
	v_add_f32_e32 v204, v204, v60
	v_add_f32_e32 v205, v205, v61
	v_add_f32_e32 v208, v208, v62
	v_add_f32_e32 v209, v209, v63
	v_add_f32_e32 v204, v204, v205
	v_add_f32_e32 v208, v208, v209
	v_add_f32_e32 v204, v204, v208
	v_add_f32_e32 v124, v124, v204
	s_branch .Lmsk_tail
